# up-GEMM epilogue: four counted waits on the conv weights (gate columns 0-3, value 0-3, gate 4-7, value 4-7)
# baseline (speedup 1.0000x reference)
; __device__ __forceinline__ unsigned cvt_pk_bf16(float lo, float hi) { unsigned r; asm volatile("v_cvt_pk_bf16_f32 %0, %1, %2" : "=v"(r) : "v"(lo), "v"(hi)); return r; }
;     __device__ __forceinline__ void operator()(f32x4 (&acc)[2][2][4][2], const Unit& u, int wr, int wc, int fr, int fq, const LAS float* rtab) const {
;     ...
;             for (int m = 0; m < 4; ++m) { const float r = rtab[ai * HALF + wr * 64 + m * 16 + fr];
; #pragma unroll
;                 for (int bj = 0; bj < 2; ++bj)
; #pragma unroll
;                     for (int n = 0; n < 2; ++n) acc[ai][bj][m][n] = acc[ai][bj][m][n] * r; }
; #pragma unroll
;         for (int ai = 0; ai < 2; ++ai) {
;             const int blk = (u.pm * BM + ai * HALF + wr * 64) >> 6;
;             if (fr < 2) { bf16_t* rp = raw + ((size_t)blk * 4 + fr) * UP_N + c0;
;                 const f32x4 g0 = acc[ai][0][0][0], g1 = acc[ai][0][0][1], u0 = acc[ai][1][0][0], u1 = acc[ai][1][0][1];
;                 u32x4 w; w.x = cvt_pk_bf16(g0[0], g0[1]); w.y = cvt_pk_bf16(g0[2], g0[3]); w.z = cvt_pk_bf16(g1[0], g1[1]); w.w = cvt_pk_bf16(g1[2], g1[3]); *(u32x4*)rp = w;
;                 w.x = cvt_pk_bf16(u0[0], u0[1]); w.y = cvt_pk_bf16(u0[2], u0[3]); w.z = cvt_pk_bf16(u1[0], u1[1]); w.w = cvt_pk_bf16(u1[2], u1[3]); *(u32x4*)(rp + DFF) = w; }
;             if (fr >= 14) { bf16_t* rp = raw + ((size_t)blk * 4 + (fr - 12)) * UP_N + c0;
;                 const f32x4 g0 = acc[ai][0][3][0], g1 = acc[ai][0][3][1], u0 = acc[ai][1][3][0], u1 = acc[ai][1][3][1];
;                 u32x4 w; w.x = cvt_pk_bf16(g0[0], g0[1]); w.y = cvt_pk_bf16(g0[2], g0[3]); w.z = cvt_pk_bf16(g1[0], g1[1]); w.w = cvt_pk_bf16(g1[2], g1[3]); *(u32x4*)rp = w;
;                 w.x = cvt_pk_bf16(u0[0], u0[1]); w.y = cvt_pk_bf16(u0[2], u0[3]); w.z = cvt_pk_bf16(u1[0], u1[1]); w.w = cvt_pk_bf16(u1[2], u1[3]); *(u32x4*)(rp + DFF) = w; }
;         }
;         u32x2 ypk[2][4];
; #pragma unroll
;         for (int n = 0; n < 2; ++n) {
;             const int cn = c0 + 4 * n;
;             const f32x4 wg0 = *(const f32x4*)(cw + cn), wg1 = *(const f32x4*)(cw + UP_N + cn), wg2 = *(const f32x4*)(cw + 2 * UP_N + cn), bg = *(const f32x4*)(cb + cn);
;             const f32x4 wu0 = *(const f32x4*)(cw + DFF + cn), wu1 = *(const f32x4*)(cw + UP_N + DFF + cn), wu2 = *(const f32x4*)(cw + 2 * UP_N + DFF + cn), bu = *(const f32x4*)(cb + DFF + cn);
.LBB0_839:
	v_lshl_add_u32 v252, s1, 10, v192
	v_mad_u32_u24 v252, v134, 12, v252
	ds_read_b128 v[228:231], v252
	ds_read_b128 v[232:235], v252 offset:512
	v_lshl_or_b32 v213, s0, 7, v193
	v_lshlrev_b32_e32 v253, 2, v213
	global_load_dwordx4 v[144:147], v253, s[34:35]
	global_load_dwordx4 v[152:155], v253, s[40:41]
	global_load_dwordx4 v[160:163], v253, s[42:43]
	global_load_dwordx4 v[168:171], v253, s[36:37]
	global_load_dwordx4 v[180:183], v253, s[44:45]
	global_load_dwordx4 v[188:191], v253, s[46:47]
	global_load_dwordx4 v[200:203], v253, s[48:49]
	global_load_dwordx4 v[220:223], v253, s[50:51]
	global_load_dwordx4 v[148:151], v253, s[34:35] offset:16
	global_load_dwordx4 v[156:159], v253, s[40:41] offset:16
	global_load_dwordx4 v[164:167], v253, s[42:43] offset:16
	global_load_dwordx4 v[172:175], v253, s[36:37] offset:16
	global_load_dwordx4 v[184:187], v253, s[44:45] offset:16
	global_load_dwordx4 v[196:199], v253, s[46:47] offset:16
	global_load_dwordx4 v[204:207], v253, s[48:49] offset:16
	global_load_dwordx4 v[224:227], v253, s[50:51] offset:16
	s_waitcnt lgkmcnt(0)
	v_pk_mul_f32 v[124:125], v[124:125], v[228:229] op_sel_hi:[1,0]
	v_pk_mul_f32 v[126:127], v[126:127], v[228:229] op_sel_hi:[1,0]
	v_pk_mul_f32 v[120:121], v[120:121], v[228:229] op_sel_hi:[1,0]
	v_pk_mul_f32 v[122:123], v[122:123], v[228:229] op_sel_hi:[1,0]
	v_pk_mul_f32 v[116:117], v[116:117], v[228:229] op_sel_hi:[1,0]
	v_pk_mul_f32 v[118:119], v[118:119], v[228:229] op_sel_hi:[1,0]
	v_pk_mul_f32 v[112:113], v[112:113], v[228:229] op_sel_hi:[1,0]
	v_pk_mul_f32 v[114:115], v[114:115], v[228:229] op_sel_hi:[1,0]
	v_pk_mul_f32 v[68:69], v[68:69], v[228:229] op_sel:[0,1] op_sel_hi:[1,1]
	v_pk_mul_f32 v[70:71], v[70:71], v[228:229] op_sel:[0,1] op_sel_hi:[1,1]
	v_pk_mul_f32 v[64:65], v[64:65], v[228:229] op_sel:[0,1] op_sel_hi:[1,1]
	v_pk_mul_f32 v[66:67], v[66:67], v[228:229] op_sel:[0,1] op_sel_hi:[1,1]
	v_pk_mul_f32 v[52:53], v[52:53], v[228:229] op_sel:[0,1] op_sel_hi:[1,1]
	v_pk_mul_f32 v[54:55], v[54:55], v[228:229] op_sel:[0,1] op_sel_hi:[1,1]
	v_pk_mul_f32 v[48:49], v[48:49], v[228:229] op_sel:[0,1] op_sel_hi:[1,1]
	v_pk_mul_f32 v[50:51], v[50:51], v[228:229] op_sel:[0,1] op_sel_hi:[1,1]
	v_pk_mul_f32 v[60:61], v[60:61], v[230:231] op_sel_hi:[1,0]
	v_pk_mul_f32 v[62:63], v[62:63], v[230:231] op_sel_hi:[1,0]
	v_pk_mul_f32 v[20:21], v[20:21], v[230:231] op_sel_hi:[1,0]
	v_pk_mul_f32 v[22:23], v[22:23], v[230:231] op_sel_hi:[1,0]
	v_pk_mul_f32 v[44:45], v[44:45], v[230:231] op_sel_hi:[1,0]
	v_pk_mul_f32 v[46:47], v[46:47], v[230:231] op_sel_hi:[1,0]
	v_pk_mul_f32 v[16:17], v[16:17], v[230:231] op_sel_hi:[1,0]
	v_pk_mul_f32 v[18:19], v[18:19], v[230:231] op_sel_hi:[1,0]
	v_pk_mul_f32 v[108:109], v[108:109], v[230:231] op_sel:[0,1] op_sel_hi:[1,1]
	v_pk_mul_f32 v[110:111], v[110:111], v[230:231] op_sel:[0,1] op_sel_hi:[1,1]
	v_pk_mul_f32 v[104:105], v[104:105], v[230:231] op_sel:[0,1] op_sel_hi:[1,1]
	v_pk_mul_f32 v[106:107], v[106:107], v[230:231] op_sel:[0,1] op_sel_hi:[1,1]
	v_pk_mul_f32 v[100:101], v[100:101], v[230:231] op_sel:[0,1] op_sel_hi:[1,1]
	v_pk_mul_f32 v[102:103], v[102:103], v[230:231] op_sel:[0,1] op_sel_hi:[1,1]
	v_pk_mul_f32 v[96:97], v[96:97], v[230:231] op_sel:[0,1] op_sel_hi:[1,1]
	v_pk_mul_f32 v[98:99], v[98:99], v[230:231] op_sel:[0,1] op_sel_hi:[1,1]
	v_pk_mul_f32 v[92:93], v[92:93], v[232:233] op_sel_hi:[1,0]
	v_pk_mul_f32 v[94:95], v[94:95], v[232:233] op_sel_hi:[1,0]
	v_pk_mul_f32 v[88:89], v[88:89], v[232:233] op_sel_hi:[1,0]
	v_pk_mul_f32 v[90:91], v[90:91], v[232:233] op_sel_hi:[1,0]
	v_pk_mul_f32 v[84:85], v[84:85], v[232:233] op_sel_hi:[1,0]
	v_pk_mul_f32 v[86:87], v[86:87], v[232:233] op_sel_hi:[1,0]
	v_pk_mul_f32 v[80:81], v[80:81], v[232:233] op_sel_hi:[1,0]
	v_pk_mul_f32 v[82:83], v[82:83], v[232:233] op_sel_hi:[1,0]
	v_pk_mul_f32 v[36:37], v[36:37], v[232:233] op_sel:[0,1] op_sel_hi:[1,1]
	v_pk_mul_f32 v[38:39], v[38:39], v[232:233] op_sel:[0,1] op_sel_hi:[1,1]
	v_pk_mul_f32 v[12:13], v[12:13], v[232:233] op_sel:[0,1] op_sel_hi:[1,1]
	v_pk_mul_f32 v[14:15], v[14:15], v[232:233] op_sel:[0,1] op_sel_hi:[1,1]
	v_pk_mul_f32 v[28:29], v[28:29], v[232:233] op_sel:[0,1] op_sel_hi:[1,1]
	v_pk_mul_f32 v[30:31], v[30:31], v[232:233] op_sel:[0,1] op_sel_hi:[1,1]
	v_pk_mul_f32 v[8:9], v[8:9], v[232:233] op_sel:[0,1] op_sel_hi:[1,1]
	v_pk_mul_f32 v[10:11], v[10:11], v[232:233] op_sel:[0,1] op_sel_hi:[1,1]
	v_pk_mul_f32 v[32:33], v[32:33], v[234:235] op_sel_hi:[1,0]
	v_pk_mul_f32 v[34:35], v[34:35], v[234:235] op_sel_hi:[1,0]
	v_pk_mul_f32 v[4:5], v[4:5], v[234:235] op_sel_hi:[1,0]
	v_pk_mul_f32 v[6:7], v[6:7], v[234:235] op_sel_hi:[1,0]
	v_pk_mul_f32 v[24:25], v[24:25], v[234:235] op_sel_hi:[1,0]
	v_pk_mul_f32 v[26:27], v[26:27], v[234:235] op_sel_hi:[1,0]
	v_pk_mul_f32 v[0:1], v[0:1], v[234:235] op_sel_hi:[1,0]
	v_pk_mul_f32 v[2:3], v[2:3], v[234:235] op_sel_hi:[1,0]
	v_pk_mul_f32 v[76:77], v[76:77], v[234:235] op_sel:[0,1] op_sel_hi:[1,1]
	v_pk_mul_f32 v[78:79], v[78:79], v[234:235] op_sel:[0,1] op_sel_hi:[1,1]
	v_pk_mul_f32 v[56:57], v[56:57], v[234:235] op_sel:[0,1] op_sel_hi:[1,1]
	v_pk_mul_f32 v[58:59], v[58:59], v[234:235] op_sel:[0,1] op_sel_hi:[1,1]
	v_pk_mul_f32 v[72:73], v[72:73], v[234:235] op_sel:[0,1] op_sel_hi:[1,1]
	v_pk_mul_f32 v[74:75], v[74:75], v[234:235] op_sel:[0,1] op_sel_hi:[1,1]
	v_pk_mul_f32 v[40:41], v[40:41], v[234:235] op_sel:[0,1] op_sel_hi:[1,1]
	v_pk_mul_f32 v[42:43], v[42:43], v[234:235] op_sel:[0,1] op_sel_hi:[1,1]
	v_lshlrev_b32_e32 v235, 1, v213
	s_lshl_b32 s0, s18, 8
	s_add_i32 s0, s0, s69
	v_lshl_add_u32 v234, v134, 2, s0
	v_mul_lo_u32 v234, v234, s89
	v_add_u32_e32 v234, v234, v235
;     __device__ __forceinline__ void operator()(f32x4 (&acc)[2][2][4][2], const Unit& u, int wr, int wc, int fr, int fq, const LAS float* rtab) const {
;     ...
;         for (int ai = 0; ai < 2; ++ai) {
;             const int blk = (u.pm * BM + ai * HALF + wr * 64) >> 6;
;             if (fr < 2) { bf16_t* rp = raw + ((size_t)blk * 4 + fr) * UP_N + c0;
;                 const f32x4 g0 = acc[ai][0][0][0], g1 = acc[ai][0][0][1], u0 = acc[ai][1][0][0], u1 = acc[ai][1][0][1];
;                 u32x4 w; w.x = cvt_pk_bf16(g0[0], g0[1]); w.y = cvt_pk_bf16(g0[2], g0[3]); w.z = cvt_pk_bf16(g1[0], g1[1]); w.w = cvt_pk_bf16(g1[2], g1[3]); *(u32x4*)rp = w;
;                 w.x = cvt_pk_bf16(u0[0], u0[1]); w.y = cvt_pk_bf16(u0[2], u0[3]); w.z = cvt_pk_bf16(u1[0], u1[1]); w.w = cvt_pk_bf16(u1[2], u1[3]); *(u32x4*)(rp + DFF) = w; }
;             if (fr >= 14) { bf16_t* rp = raw + ((size_t)blk * 4 + (fr - 12)) * UP_N + c0;
;                 const f32x4 g0 = acc[ai][0][3][0], g1 = acc[ai][0][3][1], u0 = acc[ai][1][3][0], u1 = acc[ai][1][3][1];
;                 u32x4 w; w.x = cvt_pk_bf16(g0[0], g0[1]); w.y = cvt_pk_bf16(g0[2], g0[3]); w.z = cvt_pk_bf16(g1[0], g1[1]); w.w = cvt_pk_bf16(g1[2], g1[3]); *(u32x4*)rp = w;
;                 w.x = cvt_pk_bf16(u0[0], u0[1]); w.y = cvt_pk_bf16(u0[2], u0[3]); w.z = cvt_pk_bf16(u1[0], u1[1]); w.w = cvt_pk_bf16(u1[2], u1[3]); *(u32x4*)(rp + DFF) = w; }
;         }
;     ...
;                     for (int jj = 0; jj < 4; ++jj) {
;                         const float gc = acc[ai][0][m][n][jj], uc = acc[ai][1][m][n][jj];
;                         const float gb = m > 0 ? acc[ai][0][m - 1][n][jj] : 0.f, ga = m < 3 ? acc[ai][0][m + 1][n][jj] : 0.f;
;                         const float ub = m > 0 ? acc[ai][1][m - 1][n][jj] : 0.f, ua = m < 3 ? acc[ai][1][m + 1][n][jj] : 0.f;
;                         const float gp = dppz<0x111>(gc) + dppz<0x10F>(gb), gn = dppz<0x101>(gc) + dppz<0x11F>(ga);
;                         const float up = dppz<0x111>(uc) + dppz<0x10F>(ub), un = dppz<0x101>(uc) + dppz<0x11F>(ua);
;                         const float hg = wg0[jj] * gp + wg1[jj] * gc + wg2[jj] * gn + bg[jj];
;                         const float hu = wu0[jj] * up + wu1[jj] * uc + wu2[jj] * un + bu[jj];
;                         const float sg = __builtin_amdgcn_rcpf(1.f + __builtin_amdgcn_exp2f(-1.4426950408889634f * hg));
	v_cmp_eq_u32_e64 s[54:55], 0, v134
	v_cmp_eq_u32_e64 s[56:57], 15, v134
	s_lshl_b32 s0, s18, 4
	s_lshr_b32 s1, s69, 4
	s_add_i32 s0, s0, s1
	s_add_i32 s1, s0, 0
	s_mul_i32 s1, s1, s88
	s_add_u32 s58, s30, s1
	s_addc_u32 s59, s31, 0
	s_mov_b64 exec, s[54:55]
	v_cvt_pk_bf16_f32 v244, v124, v125
	v_cvt_pk_bf16_f32 v245, v126, v127
	v_cvt_pk_bf16_f32 v246, v120, v121
	v_cvt_pk_bf16_f32 v247, v122, v123
	v_cvt_pk_bf16_f32 v248, v116, v117
	v_cvt_pk_bf16_f32 v249, v118, v119
	v_cvt_pk_bf16_f32 v250, v112, v113
	v_cvt_pk_bf16_f32 v251, v114, v115
	global_store_dwordx4 v235, v[244:247], s[58:59]
	s_add_u32 s58, s58, 0x2c00
	s_addc_u32 s59, s59, 0
	global_store_dwordx4 v235, v[248:251], s[58:59]
	s_add_i32 s1, s0, 1
	s_mul_i32 s1, s1, s88
	s_add_u32 s58, s30, s1
	s_addc_u32 s59, s31, 0
	s_mov_b64 exec, s[54:55]
	v_cvt_pk_bf16_f32 v236, v68, v69
	v_cvt_pk_bf16_f32 v237, v70, v71
	v_cvt_pk_bf16_f32 v238, v64, v65
	v_cvt_pk_bf16_f32 v239, v66, v67
	v_cvt_pk_bf16_f32 v240, v52, v53
	v_cvt_pk_bf16_f32 v241, v54, v55
	v_cvt_pk_bf16_f32 v242, v48, v49
	v_cvt_pk_bf16_f32 v243, v50, v51
	global_store_dwordx4 v235, v[236:239], s[58:59]
	s_add_u32 s58, s58, 0x2c00
	s_addc_u32 s59, s59, 0
	global_store_dwordx4 v235, v[240:243], s[58:59]
	s_add_i32 s1, s0, 2
	s_mul_i32 s1, s1, s88
	s_add_u32 s58, s30, s1
	s_addc_u32 s59, s31, 0
	s_mov_b64 exec, s[56:57]
	v_cvt_pk_bf16_f32 v244, v60, v61
	v_cvt_pk_bf16_f32 v245, v62, v63
	v_cvt_pk_bf16_f32 v246, v20, v21
	v_cvt_pk_bf16_f32 v247, v22, v23
	v_cvt_pk_bf16_f32 v248, v44, v45
	v_cvt_pk_bf16_f32 v249, v46, v47
	v_cvt_pk_bf16_f32 v250, v16, v17
	v_cvt_pk_bf16_f32 v251, v18, v19
	global_store_dwordx4 v235, v[244:247], s[58:59]
	s_add_u32 s58, s58, 0x2c00
	s_addc_u32 s59, s59, 0
	global_store_dwordx4 v235, v[248:251], s[58:59]
	s_add_i32 s1, s0, 3
	s_mul_i32 s1, s1, s88
	s_add_u32 s58, s30, s1
	s_addc_u32 s59, s31, 0
	s_mov_b64 exec, s[56:57]
	v_cvt_pk_bf16_f32 v236, v108, v109
	v_cvt_pk_bf16_f32 v237, v110, v111
	v_cvt_pk_bf16_f32 v238, v104, v105
	v_cvt_pk_bf16_f32 v239, v106, v107
	v_cvt_pk_bf16_f32 v240, v100, v101
	v_cvt_pk_bf16_f32 v241, v102, v103
	v_cvt_pk_bf16_f32 v242, v96, v97
	v_cvt_pk_bf16_f32 v243, v98, v99
	global_store_dwordx4 v235, v[236:239], s[58:59]
	s_add_u32 s58, s58, 0x2c00
	s_addc_u32 s59, s59, 0
	global_store_dwordx4 v235, v[240:243], s[58:59]
	s_add_i32 s1, s0, 8
	s_mul_i32 s1, s1, s88
	s_add_u32 s58, s30, s1
	s_addc_u32 s59, s31, 0
	s_mov_b64 exec, s[54:55]
	v_cvt_pk_bf16_f32 v244, v92, v93
	v_cvt_pk_bf16_f32 v245, v94, v95
	v_cvt_pk_bf16_f32 v246, v88, v89
	v_cvt_pk_bf16_f32 v247, v90, v91
	v_cvt_pk_bf16_f32 v248, v84, v85
	v_cvt_pk_bf16_f32 v249, v86, v87
	v_cvt_pk_bf16_f32 v250, v80, v81
	v_cvt_pk_bf16_f32 v251, v82, v83
	global_store_dwordx4 v235, v[244:247], s[58:59]
	s_add_u32 s58, s58, 0x2c00
	s_addc_u32 s59, s59, 0
	global_store_dwordx4 v235, v[248:251], s[58:59]
	s_add_i32 s1, s0, 9
	s_mul_i32 s1, s1, s88
	s_add_u32 s58, s30, s1
	s_addc_u32 s59, s31, 0
	s_mov_b64 exec, s[54:55]
	v_cvt_pk_bf16_f32 v236, v36, v37
	v_cvt_pk_bf16_f32 v237, v38, v39
	v_cvt_pk_bf16_f32 v238, v12, v13
	v_cvt_pk_bf16_f32 v239, v14, v15
	v_cvt_pk_bf16_f32 v240, v28, v29
	v_cvt_pk_bf16_f32 v241, v30, v31
	v_cvt_pk_bf16_f32 v242, v8, v9
	v_cvt_pk_bf16_f32 v243, v10, v11
	global_store_dwordx4 v235, v[236:239], s[58:59]
	s_add_u32 s58, s58, 0x2c00
	s_addc_u32 s59, s59, 0
	global_store_dwordx4 v235, v[240:243], s[58:59]
	s_add_i32 s1, s0, 10
	s_mul_i32 s1, s1, s88
	s_add_u32 s58, s30, s1
	s_addc_u32 s59, s31, 0
	s_mov_b64 exec, s[56:57]
	v_cvt_pk_bf16_f32 v244, v32, v33
	v_cvt_pk_bf16_f32 v245, v34, v35
	v_cvt_pk_bf16_f32 v246, v4, v5
	v_cvt_pk_bf16_f32 v247, v6, v7
	v_cvt_pk_bf16_f32 v248, v24, v25
	v_cvt_pk_bf16_f32 v249, v26, v27
	v_cvt_pk_bf16_f32 v250, v0, v1
	v_cvt_pk_bf16_f32 v251, v2, v3
	global_store_dwordx4 v235, v[244:247], s[58:59]
	s_add_u32 s58, s58, 0x2c00
	s_addc_u32 s59, s59, 0
	global_store_dwordx4 v235, v[248:251], s[58:59]
	s_add_i32 s1, s0, 11
	s_mul_i32 s1, s1, s88
	s_add_u32 s58, s30, s1
	s_addc_u32 s59, s31, 0
	s_mov_b64 exec, s[56:57]
	v_cvt_pk_bf16_f32 v236, v76, v77
	v_cvt_pk_bf16_f32 v237, v78, v79
	v_cvt_pk_bf16_f32 v238, v56, v57
	v_cvt_pk_bf16_f32 v239, v58, v59
	v_cvt_pk_bf16_f32 v240, v72, v73
	v_cvt_pk_bf16_f32 v241, v74, v75
	v_cvt_pk_bf16_f32 v242, v40, v41
	v_cvt_pk_bf16_f32 v243, v42, v43
	global_store_dwordx4 v235, v[236:239], s[58:59]
	s_add_u32 s58, s58, 0x2c00
	s_addc_u32 s59, s59, 0
	global_store_dwordx4 v235, v[240:243], s[58:59]
	s_mov_b64 exec, -1
	s_waitcnt vmcnt(28)
	s_mov_b32 s54, 0xbfb8aa3b
	s_mov_b32 s56, 1.0
	v_pk_fma_f32 v[142:143], v[152:153], v[124:125], v[168:169]
	v_pk_fma_f32 v[178:179], v[152:153], v[68:69], v[168:169]
	v_pk_fma_f32 v[210:211], v[152:153], v[60:61], v[168:169]
	v_pk_fma_f32 v[212:213], v[152:153], v[108:109], v[168:169]
	v_pk_fma_f32 v[142:143], v[160:161], v[68:69], v[142:143]
	v_pk_fma_f32 v[178:179], v[144:145], v[124:125], v[178:179]
	v_pk_fma_f32 v[210:211], v[144:145], v[68:69], v[210:211]
	v_pk_fma_f32 v[212:213], v[144:145], v[60:61], v[212:213]
	v_pk_fma_f32 v[178:179], v[160:161], v[60:61], v[178:179]
	v_pk_fma_f32 v[210:211], v[160:161], v[108:109], v[210:211]
	v_fmac_f32_dpp v142, v108, v144 row_shr:1 row_mask:0xf bank_mask:0xf bound_ctrl:1
	v_fmac_f32_dpp v212, v124, v160 row_shl:1 row_mask:0xf bank_mask:0xf bound_ctrl:1
	v_fmac_f32_dpp v143, v109, v145 row_shr:1 row_mask:0xf bank_mask:0xf bound_ctrl:1
	v_fmac_f32_dpp v213, v125, v161 row_shl:1 row_mask:0xf bank_mask:0xf bound_ctrl:1
	v_pk_mul_f32 v[218:219], v[142:143], s[54:55] op_sel_hi:[1,0]
	v_pk_mul_f32 v[252:253], v[178:179], s[54:55] op_sel_hi:[1,0]
	v_pk_mul_f32 v[228:229], v[210:211], s[54:55] op_sel_hi:[1,0]
	v_pk_mul_f32 v[230:231], v[212:213], s[54:55] op_sel_hi:[1,0]
	v_exp_f32_e32 v218, v218
	v_exp_f32_e32 v219, v219
	v_exp_f32_e32 v252, v252
	v_exp_f32_e32 v253, v253
	v_exp_f32_e32 v228, v228
	v_exp_f32_e32 v229, v229
	v_exp_f32_e32 v230, v230
	v_exp_f32_e32 v231, v231
	v_pk_add_f32 v[218:219], v[218:219], s[56:57] op_sel_hi:[1,0]
	v_pk_add_f32 v[252:253], v[252:253], s[56:57] op_sel_hi:[1,0]
	v_pk_add_f32 v[228:229], v[228:229], s[56:57] op_sel_hi:[1,0]
	v_pk_add_f32 v[230:231], v[230:231], s[56:57] op_sel_hi:[1,0]
	v_rcp_f32_e32 v218, v218
	v_rcp_f32_e32 v219, v219
	v_rcp_f32_e32 v252, v252
	v_rcp_f32_e32 v253, v253
	v_rcp_f32_e32 v228, v228
	v_rcp_f32_e32 v229, v229
	v_rcp_f32_e32 v230, v230
	v_rcp_f32_e32 v231, v231
	v_pk_mul_f32 v[142:143], v[142:143], v[218:219]
	v_pk_mul_f32 v[178:179], v[178:179], v[252:253]
	v_pk_mul_f32 v[210:211], v[210:211], v[228:229]
	v_pk_mul_f32 v[212:213], v[212:213], v[230:231]
	s_waitcnt vmcnt(24)
; __device__ __forceinline__ unsigned cvt_pk_bf16(float lo, float hi) { unsigned r; asm volatile("v_cvt_pk_bf16_f32 %0, %1, %2" : "=v"(r) : "v"(lo), "v"(hi)); return r; }
; template <int CTRL> __device__ __forceinline__ float dppz(float v) { return __int_as_float(__builtin_amdgcn_update_dpp(0, __float_as_int(v), CTRL, 0xf, 0xf, true)); }
;     __device__ __forceinline__ void operator()(f32x4 (&acc)[2][2][4][2], const Unit& u, int wr, int wc, int fr, int fq, const LAS float* rtab) const {
;     ...
;                     for (int jj = 0; jj < 4; ++jj) {
;                         const float gc = acc[ai][0][m][n][jj], uc = acc[ai][1][m][n][jj];
;                         const float gb = m > 0 ? acc[ai][0][m - 1][n][jj] : 0.f, ga = m < 3 ? acc[ai][0][m + 1][n][jj] : 0.f;
;                         const float ub = m > 0 ? acc[ai][1][m - 1][n][jj] : 0.f, ua = m < 3 ? acc[ai][1][m + 1][n][jj] : 0.f;
;                         const float gp = dppz<0x111>(gc) + dppz<0x10F>(gb), gn = dppz<0x101>(gc) + dppz<0x11F>(ga);
;                         const float up = dppz<0x111>(uc) + dppz<0x10F>(ub), un = dppz<0x101>(uc) + dppz<0x11F>(ua);
;                         const float hg = wg0[jj] * gp + wg1[jj] * gc + wg2[jj] * gn + bg[jj];
;                         const float hu = wu0[jj] * up + wu1[jj] * uc + wu2[jj] * un + bu[jj];
;                         const float sg = __builtin_amdgcn_rcpf(1.f + __builtin_amdgcn_exp2f(-1.4426950408889634f * hg));
;                         y[jj] = hg * sg * hu; }
;                     u32x2 pk; pk.x = cvt_pk_bf16(y[0], y[1]); pk.y = cvt_pk_bf16(y[2], y[3]);
	v_pk_fma_f32 v[218:219], v[188:189], v[116:117], v[220:221]
	v_pk_fma_f32 v[252:253], v[188:189], v[52:53], v[220:221]
	v_pk_fma_f32 v[228:229], v[188:189], v[44:45], v[220:221]
	v_pk_fma_f32 v[230:231], v[188:189], v[100:101], v[220:221]
	v_pk_fma_f32 v[218:219], v[200:201], v[52:53], v[218:219]
	v_pk_fma_f32 v[252:253], v[180:181], v[116:117], v[252:253]
	v_pk_fma_f32 v[228:229], v[180:181], v[52:53], v[228:229]
	v_pk_fma_f32 v[230:231], v[180:181], v[44:45], v[230:231]
	v_pk_fma_f32 v[252:253], v[200:201], v[44:45], v[252:253]
	v_pk_fma_f32 v[228:229], v[200:201], v[100:101], v[228:229]
	v_fmac_f32_dpp v218, v100, v180 row_shr:1 row_mask:0xf bank_mask:0xf bound_ctrl:1
	v_fmac_f32_dpp v230, v116, v200 row_shl:1 row_mask:0xf bank_mask:0xf bound_ctrl:1
	v_fmac_f32_dpp v219, v101, v181 row_shr:1 row_mask:0xf bank_mask:0xf bound_ctrl:1
	v_fmac_f32_dpp v231, v117, v201 row_shl:1 row_mask:0xf bank_mask:0xf bound_ctrl:1
	v_pk_mul_f32 v[142:143], v[142:143], v[218:219]
	v_pk_mul_f32 v[178:179], v[178:179], v[252:253]
	v_pk_mul_f32 v[210:211], v[210:211], v[228:229]
	v_pk_mul_f32 v[212:213], v[212:213], v[230:231]
	v_cvt_pk_bf16_f32 v236, v142, v143
	v_cvt_pk_bf16_f32 v240, v178, v179
	v_cvt_pk_bf16_f32 v244, v210, v211
	v_cvt_pk_bf16_f32 v248, v212, v213
	v_pk_fma_f32 v[142:143], v[154:155], v[126:127], v[170:171]
	v_pk_fma_f32 v[178:179], v[154:155], v[70:71], v[170:171]
	v_pk_fma_f32 v[210:211], v[154:155], v[62:63], v[170:171]
	v_pk_fma_f32 v[212:213], v[154:155], v[110:111], v[170:171]
	v_pk_fma_f32 v[142:143], v[162:163], v[70:71], v[142:143]
	v_pk_fma_f32 v[178:179], v[146:147], v[126:127], v[178:179]
	v_pk_fma_f32 v[210:211], v[146:147], v[70:71], v[210:211]
	v_pk_fma_f32 v[212:213], v[146:147], v[62:63], v[212:213]
	v_pk_fma_f32 v[178:179], v[162:163], v[62:63], v[178:179]
	v_pk_fma_f32 v[210:211], v[162:163], v[110:111], v[210:211]
	v_fmac_f32_dpp v142, v110, v146 row_shr:1 row_mask:0xf bank_mask:0xf bound_ctrl:1
	v_fmac_f32_dpp v212, v126, v162 row_shl:1 row_mask:0xf bank_mask:0xf bound_ctrl:1
	v_fmac_f32_dpp v143, v111, v147 row_shr:1 row_mask:0xf bank_mask:0xf bound_ctrl:1
	v_fmac_f32_dpp v213, v127, v163 row_shl:1 row_mask:0xf bank_mask:0xf bound_ctrl:1
	v_pk_mul_f32 v[218:219], v[142:143], s[54:55] op_sel_hi:[1,0]
	v_pk_mul_f32 v[252:253], v[178:179], s[54:55] op_sel_hi:[1,0]
	v_pk_mul_f32 v[228:229], v[210:211], s[54:55] op_sel_hi:[1,0]
	v_pk_mul_f32 v[230:231], v[212:213], s[54:55] op_sel_hi:[1,0]
	v_exp_f32_e32 v218, v218
	v_exp_f32_e32 v219, v219
	v_exp_f32_e32 v252, v252
	v_exp_f32_e32 v253, v253
	v_exp_f32_e32 v228, v228
	v_exp_f32_e32 v229, v229
	v_exp_f32_e32 v230, v230
	v_exp_f32_e32 v231, v231
	v_pk_add_f32 v[218:219], v[218:219], s[56:57] op_sel_hi:[1,0]
	v_pk_add_f32 v[252:253], v[252:253], s[56:57] op_sel_hi:[1,0]
	v_pk_add_f32 v[228:229], v[228:229], s[56:57] op_sel_hi:[1,0]
	v_pk_add_f32 v[230:231], v[230:231], s[56:57] op_sel_hi:[1,0]
	v_rcp_f32_e32 v218, v218
	v_rcp_f32_e32 v219, v219
	v_rcp_f32_e32 v252, v252
	v_rcp_f32_e32 v253, v253
	v_rcp_f32_e32 v228, v228
	v_rcp_f32_e32 v229, v229
	v_rcp_f32_e32 v230, v230
	v_rcp_f32_e32 v231, v231
	v_pk_mul_f32 v[142:143], v[142:143], v[218:219]
	v_pk_mul_f32 v[178:179], v[178:179], v[252:253]
	v_pk_mul_f32 v[210:211], v[210:211], v[228:229]
	v_pk_mul_f32 v[212:213], v[212:213], v[230:231]
	v_pk_fma_f32 v[218:219], v[190:191], v[118:119], v[222:223]
	v_pk_fma_f32 v[252:253], v[190:191], v[54:55], v[222:223]
	v_pk_fma_f32 v[228:229], v[190:191], v[46:47], v[222:223]
	v_pk_fma_f32 v[230:231], v[190:191], v[102:103], v[222:223]
	v_pk_fma_f32 v[218:219], v[202:203], v[54:55], v[218:219]
	v_pk_fma_f32 v[252:253], v[182:183], v[118:119], v[252:253]
	v_pk_fma_f32 v[228:229], v[182:183], v[54:55], v[228:229]
	v_pk_fma_f32 v[230:231], v[182:183], v[46:47], v[230:231]
	v_pk_fma_f32 v[252:253], v[202:203], v[46:47], v[252:253]
	v_pk_fma_f32 v[228:229], v[202:203], v[102:103], v[228:229]
	v_fmac_f32_dpp v218, v102, v182 row_shr:1 row_mask:0xf bank_mask:0xf bound_ctrl:1
	v_fmac_f32_dpp v230, v118, v202 row_shl:1 row_mask:0xf bank_mask:0xf bound_ctrl:1
	v_fmac_f32_dpp v219, v103, v183 row_shr:1 row_mask:0xf bank_mask:0xf bound_ctrl:1
	v_fmac_f32_dpp v231, v119, v203 row_shl:1 row_mask:0xf bank_mask:0xf bound_ctrl:1
	v_pk_mul_f32 v[142:143], v[142:143], v[218:219]
	v_pk_mul_f32 v[178:179], v[178:179], v[252:253]
	v_pk_mul_f32 v[210:211], v[210:211], v[228:229]
	v_pk_mul_f32 v[212:213], v[212:213], v[230:231]
	v_cvt_pk_bf16_f32 v237, v142, v143
	v_cvt_pk_bf16_f32 v241, v178, v179
	v_cvt_pk_bf16_f32 v245, v210, v211
	v_cvt_pk_bf16_f32 v249, v212, v213
	s_waitcnt vmcnt(20)
; __device__ __forceinline__ unsigned cvt_pk_bf16(float lo, float hi) { unsigned r; asm volatile("v_cvt_pk_bf16_f32 %0, %1, %2" : "=v"(r) : "v"(lo), "v"(hi)); return r; }
; template <int CTRL> __device__ __forceinline__ float dppz(float v) { return __int_as_float(__builtin_amdgcn_update_dpp(0, __float_as_int(v), CTRL, 0xf, 0xf, true)); }
;     __device__ __forceinline__ void operator()(f32x4 (&acc)[2][2][4][2], const Unit& u, int wr, int wc, int fr, int fq, const LAS float* rtab) const {
;     ...
;                     for (int jj = 0; jj < 4; ++jj) {
;                         const float gc = acc[ai][0][m][n][jj], uc = acc[ai][1][m][n][jj];
;                         const float gb = m > 0 ? acc[ai][0][m - 1][n][jj] : 0.f, ga = m < 3 ? acc[ai][0][m + 1][n][jj] : 0.f;
;                         const float ub = m > 0 ? acc[ai][1][m - 1][n][jj] : 0.f, ua = m < 3 ? acc[ai][1][m + 1][n][jj] : 0.f;
;                         const float gp = dppz<0x111>(gc) + dppz<0x10F>(gb), gn = dppz<0x101>(gc) + dppz<0x11F>(ga);
;                         const float up = dppz<0x111>(uc) + dppz<0x10F>(ub), un = dppz<0x101>(uc) + dppz<0x11F>(ua);
;                         const float hg = wg0[jj] * gp + wg1[jj] * gc + wg2[jj] * gn + bg[jj];
;                         const float hu = wu0[jj] * up + wu1[jj] * uc + wu2[jj] * un + bu[jj];
;                         const float sg = __builtin_amdgcn_rcpf(1.f + __builtin_amdgcn_exp2f(-1.4426950408889634f * hg));
;                         y[jj] = hg * sg * hu; }
;                     u32x2 pk; pk.x = cvt_pk_bf16(y[0], y[1]); pk.y = cvt_pk_bf16(y[2], y[3]);
	v_pk_fma_f32 v[142:143], v[156:157], v[120:121], v[172:173]
	v_pk_fma_f32 v[178:179], v[156:157], v[64:65], v[172:173]
	v_pk_fma_f32 v[210:211], v[156:157], v[20:21], v[172:173]
	v_pk_fma_f32 v[212:213], v[156:157], v[104:105], v[172:173]
	v_pk_fma_f32 v[142:143], v[164:165], v[64:65], v[142:143]
	v_pk_fma_f32 v[178:179], v[148:149], v[120:121], v[178:179]
	v_pk_fma_f32 v[210:211], v[148:149], v[64:65], v[210:211]
	v_pk_fma_f32 v[212:213], v[148:149], v[20:21], v[212:213]
	v_pk_fma_f32 v[178:179], v[164:165], v[20:21], v[178:179]
	v_pk_fma_f32 v[210:211], v[164:165], v[104:105], v[210:211]
	v_fmac_f32_dpp v142, v104, v148 row_shr:1 row_mask:0xf bank_mask:0xf bound_ctrl:1
	v_fmac_f32_dpp v212, v120, v164 row_shl:1 row_mask:0xf bank_mask:0xf bound_ctrl:1
	v_fmac_f32_dpp v143, v105, v149 row_shr:1 row_mask:0xf bank_mask:0xf bound_ctrl:1
	v_fmac_f32_dpp v213, v121, v165 row_shl:1 row_mask:0xf bank_mask:0xf bound_ctrl:1
	v_pk_mul_f32 v[218:219], v[142:143], s[54:55] op_sel_hi:[1,0]
	v_pk_mul_f32 v[252:253], v[178:179], s[54:55] op_sel_hi:[1,0]
	v_pk_mul_f32 v[228:229], v[210:211], s[54:55] op_sel_hi:[1,0]
	v_pk_mul_f32 v[230:231], v[212:213], s[54:55] op_sel_hi:[1,0]
	v_exp_f32_e32 v218, v218
	v_exp_f32_e32 v219, v219
	v_exp_f32_e32 v252, v252
	v_exp_f32_e32 v253, v253
	v_exp_f32_e32 v228, v228
	v_exp_f32_e32 v229, v229
	v_exp_f32_e32 v230, v230
	v_exp_f32_e32 v231, v231
	v_pk_add_f32 v[218:219], v[218:219], s[56:57] op_sel_hi:[1,0]
	v_pk_add_f32 v[252:253], v[252:253], s[56:57] op_sel_hi:[1,0]
	v_pk_add_f32 v[228:229], v[228:229], s[56:57] op_sel_hi:[1,0]
	v_pk_add_f32 v[230:231], v[230:231], s[56:57] op_sel_hi:[1,0]
	v_rcp_f32_e32 v218, v218
	v_rcp_f32_e32 v219, v219
	v_rcp_f32_e32 v252, v252
	v_rcp_f32_e32 v253, v253
	v_rcp_f32_e32 v228, v228
	v_rcp_f32_e32 v229, v229
	v_rcp_f32_e32 v230, v230
	v_rcp_f32_e32 v231, v231
	v_pk_mul_f32 v[142:143], v[142:143], v[218:219]
	v_pk_mul_f32 v[178:179], v[178:179], v[252:253]
	v_pk_mul_f32 v[210:211], v[210:211], v[228:229]
	v_pk_mul_f32 v[212:213], v[212:213], v[230:231]
	s_waitcnt vmcnt(16)
	v_pk_fma_f32 v[218:219], v[196:197], v[112:113], v[224:225]
	v_pk_fma_f32 v[252:253], v[196:197], v[48:49], v[224:225]
	v_pk_fma_f32 v[228:229], v[196:197], v[16:17], v[224:225]
	v_pk_fma_f32 v[230:231], v[196:197], v[96:97], v[224:225]
	v_pk_fma_f32 v[218:219], v[204:205], v[48:49], v[218:219]
	v_pk_fma_f32 v[252:253], v[184:185], v[112:113], v[252:253]
	v_pk_fma_f32 v[228:229], v[184:185], v[48:49], v[228:229]
	v_pk_fma_f32 v[230:231], v[184:185], v[16:17], v[230:231]
	v_pk_fma_f32 v[252:253], v[204:205], v[16:17], v[252:253]
	v_pk_fma_f32 v[228:229], v[204:205], v[96:97], v[228:229]
	v_fmac_f32_dpp v218, v96, v184 row_shr:1 row_mask:0xf bank_mask:0xf bound_ctrl:1
	v_fmac_f32_dpp v230, v112, v204 row_shl:1 row_mask:0xf bank_mask:0xf bound_ctrl:1
	v_fmac_f32_dpp v219, v97, v185 row_shr:1 row_mask:0xf bank_mask:0xf bound_ctrl:1
	v_fmac_f32_dpp v231, v113, v205 row_shl:1 row_mask:0xf bank_mask:0xf bound_ctrl:1
	v_pk_mul_f32 v[142:143], v[142:143], v[218:219]
	v_pk_mul_f32 v[178:179], v[178:179], v[252:253]
	v_pk_mul_f32 v[210:211], v[210:211], v[228:229]
	v_pk_mul_f32 v[212:213], v[212:213], v[230:231]
	v_cvt_pk_bf16_f32 v238, v142, v143
	v_cvt_pk_bf16_f32 v242, v178, v179
	v_cvt_pk_bf16_f32 v246, v210, v211
	v_cvt_pk_bf16_f32 v250, v212, v213
	v_pk_fma_f32 v[142:143], v[158:159], v[122:123], v[174:175]
	v_pk_fma_f32 v[178:179], v[158:159], v[66:67], v[174:175]
	v_pk_fma_f32 v[210:211], v[158:159], v[22:23], v[174:175]
	v_pk_fma_f32 v[212:213], v[158:159], v[106:107], v[174:175]
	v_pk_fma_f32 v[142:143], v[166:167], v[66:67], v[142:143]
	v_pk_fma_f32 v[178:179], v[150:151], v[122:123], v[178:179]
	v_pk_fma_f32 v[210:211], v[150:151], v[66:67], v[210:211]
	v_pk_fma_f32 v[212:213], v[150:151], v[22:23], v[212:213]
	v_pk_fma_f32 v[178:179], v[166:167], v[22:23], v[178:179]
	v_pk_fma_f32 v[210:211], v[166:167], v[106:107], v[210:211]
	v_fmac_f32_dpp v142, v106, v150 row_shr:1 row_mask:0xf bank_mask:0xf bound_ctrl:1
	v_fmac_f32_dpp v212, v122, v166 row_shl:1 row_mask:0xf bank_mask:0xf bound_ctrl:1
	v_fmac_f32_dpp v143, v107, v151 row_shr:1 row_mask:0xf bank_mask:0xf bound_ctrl:1
	v_fmac_f32_dpp v213, v123, v167 row_shl:1 row_mask:0xf bank_mask:0xf bound_ctrl:1
	v_pk_mul_f32 v[218:219], v[142:143], s[54:55] op_sel_hi:[1,0]
	v_pk_mul_f32 v[252:253], v[178:179], s[54:55] op_sel_hi:[1,0]
	v_pk_mul_f32 v[228:229], v[210:211], s[54:55] op_sel_hi:[1,0]
	v_pk_mul_f32 v[230:231], v[212:213], s[54:55] op_sel_hi:[1,0]
	v_exp_f32_e32 v218, v218
	v_exp_f32_e32 v219, v219
	v_exp_f32_e32 v252, v252
	v_exp_f32_e32 v253, v253
	v_exp_f32_e32 v228, v228
	v_exp_f32_e32 v229, v229
	v_exp_f32_e32 v230, v230
	v_exp_f32_e32 v231, v231
	v_pk_add_f32 v[218:219], v[218:219], s[56:57] op_sel_hi:[1,0]
	v_pk_add_f32 v[252:253], v[252:253], s[56:57] op_sel_hi:[1,0]
	v_pk_add_f32 v[228:229], v[228:229], s[56:57] op_sel_hi:[1,0]
	v_pk_add_f32 v[230:231], v[230:231], s[56:57] op_sel_hi:[1,0]
	v_rcp_f32_e32 v218, v218
	v_rcp_f32_e32 v219, v219
	v_rcp_f32_e32 v252, v252
	v_rcp_f32_e32 v253, v253
	v_rcp_f32_e32 v228, v228
	v_rcp_f32_e32 v229, v229
	v_rcp_f32_e32 v230, v230
	v_rcp_f32_e32 v231, v231
	v_pk_mul_f32 v[142:143], v[142:143], v[218:219]
	v_pk_mul_f32 v[178:179], v[178:179], v[252:253]
	v_pk_mul_f32 v[210:211], v[210:211], v[228:229]
	v_pk_mul_f32 v[212:213], v[212:213], v[230:231]
	v_pk_fma_f32 v[218:219], v[198:199], v[114:115], v[226:227]
	v_pk_fma_f32 v[252:253], v[198:199], v[50:51], v[226:227]
	v_pk_fma_f32 v[228:229], v[198:199], v[18:19], v[226:227]
	v_pk_fma_f32 v[230:231], v[198:199], v[98:99], v[226:227]
; __device__ __forceinline__ unsigned cvt_pk_bf16(float lo, float hi) { unsigned r; asm volatile("v_cvt_pk_bf16_f32 %0, %1, %2" : "=v"(r) : "v"(lo), "v"(hi)); return r; }
; template <int CTRL> __device__ __forceinline__ float dppz(float v) { return __int_as_float(__builtin_amdgcn_update_dpp(0, __float_as_int(v), CTRL, 0xf, 0xf, true)); }
;     __device__ __forceinline__ void operator()(f32x4 (&acc)[2][2][4][2], const Unit& u, int wr, int wc, int fr, int fq, const LAS float* rtab) const {
;     ...
;                     for (int jj = 0; jj < 4; ++jj) {
;                         const float gc = acc[ai][0][m][n][jj], uc = acc[ai][1][m][n][jj];
;                         const float gb = m > 0 ? acc[ai][0][m - 1][n][jj] : 0.f, ga = m < 3 ? acc[ai][0][m + 1][n][jj] : 0.f;
;                         const float ub = m > 0 ? acc[ai][1][m - 1][n][jj] : 0.f, ua = m < 3 ? acc[ai][1][m + 1][n][jj] : 0.f;
;                         const float gp = dppz<0x111>(gc) + dppz<0x10F>(gb), gn = dppz<0x101>(gc) + dppz<0x11F>(ga);
;                         const float up = dppz<0x111>(uc) + dppz<0x10F>(ub), un = dppz<0x101>(uc) + dppz<0x11F>(ua);
;                         const float hg = wg0[jj] * gp + wg1[jj] * gc + wg2[jj] * gn + bg[jj];
;                         const float hu = wu0[jj] * up + wu1[jj] * uc + wu2[jj] * un + bu[jj];
;                         const float sg = __builtin_amdgcn_rcpf(1.f + __builtin_amdgcn_exp2f(-1.4426950408889634f * hg));
;                         y[jj] = hg * sg * hu; }
;                     u32x2 pk; pk.x = cvt_pk_bf16(y[0], y[1]); pk.y = cvt_pk_bf16(y[2], y[3]);
;                     if (n == 0) ypk[ai][m] = pk;
;                     else {
;                         const bool deferred = (m == 0 && fr == 0) || (m == 3 && fr == 15);
;                         if (!deferred) { u32x4 w; w.x = ypk[ai][m].x; w.y = ypk[ai][m].y; w.z = pk.x; w.w = pk.y; *(u32x4*)(act + (size_t)(r64 + m * 16 + fr) * DFF + c0) = w; } }
	v_pk_fma_f32 v[218:219], v[206:207], v[50:51], v[218:219]
	v_pk_fma_f32 v[252:253], v[186:187], v[114:115], v[252:253]
	v_pk_fma_f32 v[228:229], v[186:187], v[50:51], v[228:229]
	v_pk_fma_f32 v[230:231], v[186:187], v[18:19], v[230:231]
	v_pk_fma_f32 v[252:253], v[206:207], v[18:19], v[252:253]
	v_pk_fma_f32 v[228:229], v[206:207], v[98:99], v[228:229]
	v_fmac_f32_dpp v218, v98, v186 row_shr:1 row_mask:0xf bank_mask:0xf bound_ctrl:1
	v_fmac_f32_dpp v230, v114, v206 row_shl:1 row_mask:0xf bank_mask:0xf bound_ctrl:1
	v_fmac_f32_dpp v219, v99, v187 row_shr:1 row_mask:0xf bank_mask:0xf bound_ctrl:1
	v_fmac_f32_dpp v231, v115, v207 row_shl:1 row_mask:0xf bank_mask:0xf bound_ctrl:1
	v_pk_mul_f32 v[142:143], v[142:143], v[218:219]
	v_pk_mul_f32 v[178:179], v[178:179], v[252:253]
	v_pk_mul_f32 v[210:211], v[210:211], v[228:229]
	v_pk_mul_f32 v[212:213], v[212:213], v[230:231]
	v_cvt_pk_bf16_f32 v239, v142, v143
	v_cvt_pk_bf16_f32 v243, v178, v179
	v_cvt_pk_bf16_f32 v247, v210, v211
	v_cvt_pk_bf16_f32 v251, v212, v213
	s_mov_b64 s[58:59], s[28:29]
	s_mov_b64 exec, s[12:13]
	global_store_dwordx4 v234, v[236:239], s[58:59]
	s_mov_b64 exec, -1
	s_add_u32 s58, s28, 0x2c00
	s_addc_u32 s59, s29, 0
	global_store_dwordx4 v234, v[240:243], s[58:59]
	s_add_u32 s58, s28, 0x5800
	s_addc_u32 s59, s29, 0
	global_store_dwordx4 v234, v[244:247], s[58:59]
	s_add_u32 s58, s28, 0x8400
	s_addc_u32 s59, s29, 0
	s_mov_b64 exec, s[10:11]
	global_store_dwordx4 v234, v[248:251], s[58:59]
	s_mov_b64 exec, -1
	v_pk_fma_f32 v[142:143], v[152:153], v[92:93], v[168:169]
	v_pk_fma_f32 v[178:179], v[152:153], v[36:37], v[168:169]
	v_pk_fma_f32 v[210:211], v[152:153], v[32:33], v[168:169]
	v_pk_fma_f32 v[212:213], v[152:153], v[76:77], v[168:169]
	v_pk_fma_f32 v[142:143], v[160:161], v[36:37], v[142:143]
	v_pk_fma_f32 v[178:179], v[144:145], v[92:93], v[178:179]
	v_pk_fma_f32 v[210:211], v[144:145], v[36:37], v[210:211]
	v_pk_fma_f32 v[212:213], v[144:145], v[32:33], v[212:213]
	v_pk_fma_f32 v[178:179], v[160:161], v[32:33], v[178:179]
	v_pk_fma_f32 v[210:211], v[160:161], v[76:77], v[210:211]
	v_fmac_f32_dpp v142, v76, v144 row_shr:1 row_mask:0xf bank_mask:0xf bound_ctrl:1
	v_fmac_f32_dpp v212, v92, v160 row_shl:1 row_mask:0xf bank_mask:0xf bound_ctrl:1
	v_fmac_f32_dpp v143, v77, v145 row_shr:1 row_mask:0xf bank_mask:0xf bound_ctrl:1
	v_fmac_f32_dpp v213, v93, v161 row_shl:1 row_mask:0xf bank_mask:0xf bound_ctrl:1
	v_pk_mul_f32 v[218:219], v[142:143], s[54:55] op_sel_hi:[1,0]
	v_pk_mul_f32 v[252:253], v[178:179], s[54:55] op_sel_hi:[1,0]
	v_pk_mul_f32 v[228:229], v[210:211], s[54:55] op_sel_hi:[1,0]
	v_pk_mul_f32 v[230:231], v[212:213], s[54:55] op_sel_hi:[1,0]
	v_exp_f32_e32 v218, v218
	v_exp_f32_e32 v219, v219
	v_exp_f32_e32 v252, v252
	v_exp_f32_e32 v253, v253
	v_exp_f32_e32 v228, v228
	v_exp_f32_e32 v229, v229
	v_exp_f32_e32 v230, v230
	v_exp_f32_e32 v231, v231
	v_pk_add_f32 v[218:219], v[218:219], s[56:57] op_sel_hi:[1,0]
	v_pk_add_f32 v[252:253], v[252:253], s[56:57] op_sel_hi:[1,0]
	v_pk_add_f32 v[228:229], v[228:229], s[56:57] op_sel_hi:[1,0]
	v_pk_add_f32 v[230:231], v[230:231], s[56:57] op_sel_hi:[1,0]
	v_rcp_f32_e32 v218, v218
	v_rcp_f32_e32 v219, v219
	v_rcp_f32_e32 v252, v252
	v_rcp_f32_e32 v253, v253
	v_rcp_f32_e32 v228, v228
	v_rcp_f32_e32 v229, v229
	v_rcp_f32_e32 v230, v230
	v_rcp_f32_e32 v231, v231
	v_pk_mul_f32 v[142:143], v[142:143], v[218:219]
	v_pk_mul_f32 v[178:179], v[178:179], v[252:253]
	v_pk_mul_f32 v[210:211], v[210:211], v[228:229]
	v_pk_mul_f32 v[212:213], v[212:213], v[230:231]
	v_pk_fma_f32 v[218:219], v[188:189], v[84:85], v[220:221]
	v_pk_fma_f32 v[252:253], v[188:189], v[28:29], v[220:221]
	v_pk_fma_f32 v[228:229], v[188:189], v[24:25], v[220:221]
	v_pk_fma_f32 v[230:231], v[188:189], v[72:73], v[220:221]
	v_pk_fma_f32 v[218:219], v[200:201], v[28:29], v[218:219]
	v_pk_fma_f32 v[252:253], v[180:181], v[84:85], v[252:253]
	v_pk_fma_f32 v[228:229], v[180:181], v[28:29], v[228:229]
	v_pk_fma_f32 v[230:231], v[180:181], v[24:25], v[230:231]
	v_pk_fma_f32 v[252:253], v[200:201], v[24:25], v[252:253]
	v_pk_fma_f32 v[228:229], v[200:201], v[72:73], v[228:229]
	v_fmac_f32_dpp v218, v72, v180 row_shr:1 row_mask:0xf bank_mask:0xf bound_ctrl:1
	v_fmac_f32_dpp v230, v84, v200 row_shl:1 row_mask:0xf bank_mask:0xf bound_ctrl:1
	v_fmac_f32_dpp v219, v73, v181 row_shr:1 row_mask:0xf bank_mask:0xf bound_ctrl:1
	v_fmac_f32_dpp v231, v85, v201 row_shl:1 row_mask:0xf bank_mask:0xf bound_ctrl:1
	v_pk_mul_f32 v[142:143], v[142:143], v[218:219]
	v_pk_mul_f32 v[178:179], v[178:179], v[252:253]
	v_pk_mul_f32 v[210:211], v[210:211], v[228:229]
	v_pk_mul_f32 v[212:213], v[212:213], v[230:231]
	v_cvt_pk_bf16_f32 v236, v142, v143
	v_cvt_pk_bf16_f32 v240, v178, v179
	v_cvt_pk_bf16_f32 v244, v210, v211
	v_cvt_pk_bf16_f32 v248, v212, v213
	v_pk_fma_f32 v[142:143], v[154:155], v[94:95], v[170:171]
	v_pk_fma_f32 v[178:179], v[154:155], v[38:39], v[170:171]
	v_pk_fma_f32 v[210:211], v[154:155], v[34:35], v[170:171]
	v_pk_fma_f32 v[212:213], v[154:155], v[78:79], v[170:171]
	v_pk_fma_f32 v[142:143], v[162:163], v[38:39], v[142:143]
	v_pk_fma_f32 v[178:179], v[146:147], v[94:95], v[178:179]
	v_pk_fma_f32 v[210:211], v[146:147], v[38:39], v[210:211]
	v_pk_fma_f32 v[212:213], v[146:147], v[34:35], v[212:213]
	v_pk_fma_f32 v[178:179], v[162:163], v[34:35], v[178:179]
	v_pk_fma_f32 v[210:211], v[162:163], v[78:79], v[210:211]
	v_fmac_f32_dpp v142, v78, v146 row_shr:1 row_mask:0xf bank_mask:0xf bound_ctrl:1
	v_fmac_f32_dpp v212, v94, v162 row_shl:1 row_mask:0xf bank_mask:0xf bound_ctrl:1
	v_fmac_f32_dpp v143, v79, v147 row_shr:1 row_mask:0xf bank_mask:0xf bound_ctrl:1
; __device__ __forceinline__ unsigned cvt_pk_bf16(float lo, float hi) { unsigned r; asm volatile("v_cvt_pk_bf16_f32 %0, %1, %2" : "=v"(r) : "v"(lo), "v"(hi)); return r; }
; template <int CTRL> __device__ __forceinline__ float dppz(float v) { return __int_as_float(__builtin_amdgcn_update_dpp(0, __float_as_int(v), CTRL, 0xf, 0xf, true)); }
;     __device__ __forceinline__ void operator()(f32x4 (&acc)[2][2][4][2], const Unit& u, int wr, int wc, int fr, int fq, const LAS float* rtab) const {
;     ...
;                     for (int jj = 0; jj < 4; ++jj) {
;                         const float gc = acc[ai][0][m][n][jj], uc = acc[ai][1][m][n][jj];
;                         const float gb = m > 0 ? acc[ai][0][m - 1][n][jj] : 0.f, ga = m < 3 ? acc[ai][0][m + 1][n][jj] : 0.f;
;                         const float ub = m > 0 ? acc[ai][1][m - 1][n][jj] : 0.f, ua = m < 3 ? acc[ai][1][m + 1][n][jj] : 0.f;
;                         const float gp = dppz<0x111>(gc) + dppz<0x10F>(gb), gn = dppz<0x101>(gc) + dppz<0x11F>(ga);
;                         const float up = dppz<0x111>(uc) + dppz<0x10F>(ub), un = dppz<0x101>(uc) + dppz<0x11F>(ua);
;                         const float hg = wg0[jj] * gp + wg1[jj] * gc + wg2[jj] * gn + bg[jj];
;                         const float hu = wu0[jj] * up + wu1[jj] * uc + wu2[jj] * un + bu[jj];
;                         const float sg = __builtin_amdgcn_rcpf(1.f + __builtin_amdgcn_exp2f(-1.4426950408889634f * hg));
;                         y[jj] = hg * sg * hu; }
;                     u32x2 pk; pk.x = cvt_pk_bf16(y[0], y[1]); pk.y = cvt_pk_bf16(y[2], y[3]);
	v_fmac_f32_dpp v213, v95, v163 row_shl:1 row_mask:0xf bank_mask:0xf bound_ctrl:1
	v_pk_mul_f32 v[218:219], v[142:143], s[54:55] op_sel_hi:[1,0]
	v_pk_mul_f32 v[252:253], v[178:179], s[54:55] op_sel_hi:[1,0]
	v_pk_mul_f32 v[228:229], v[210:211], s[54:55] op_sel_hi:[1,0]
	v_pk_mul_f32 v[230:231], v[212:213], s[54:55] op_sel_hi:[1,0]
	v_exp_f32_e32 v218, v218
	v_exp_f32_e32 v219, v219
	v_exp_f32_e32 v252, v252
	v_exp_f32_e32 v253, v253
	v_exp_f32_e32 v228, v228
	v_exp_f32_e32 v229, v229
	v_exp_f32_e32 v230, v230
	v_exp_f32_e32 v231, v231
	v_pk_add_f32 v[218:219], v[218:219], s[56:57] op_sel_hi:[1,0]
	v_pk_add_f32 v[252:253], v[252:253], s[56:57] op_sel_hi:[1,0]
	v_pk_add_f32 v[228:229], v[228:229], s[56:57] op_sel_hi:[1,0]
	v_pk_add_f32 v[230:231], v[230:231], s[56:57] op_sel_hi:[1,0]
	v_rcp_f32_e32 v218, v218
	v_rcp_f32_e32 v219, v219
	v_rcp_f32_e32 v252, v252
	v_rcp_f32_e32 v253, v253
	v_rcp_f32_e32 v228, v228
	v_rcp_f32_e32 v229, v229
	v_rcp_f32_e32 v230, v230
	v_rcp_f32_e32 v231, v231
	v_pk_mul_f32 v[142:143], v[142:143], v[218:219]
	v_pk_mul_f32 v[178:179], v[178:179], v[252:253]
	v_pk_mul_f32 v[210:211], v[210:211], v[228:229]
	v_pk_mul_f32 v[212:213], v[212:213], v[230:231]
	v_pk_fma_f32 v[218:219], v[190:191], v[86:87], v[222:223]
	v_pk_fma_f32 v[252:253], v[190:191], v[30:31], v[222:223]
	v_pk_fma_f32 v[228:229], v[190:191], v[26:27], v[222:223]
	v_pk_fma_f32 v[230:231], v[190:191], v[74:75], v[222:223]
	v_pk_fma_f32 v[218:219], v[202:203], v[30:31], v[218:219]
	v_pk_fma_f32 v[252:253], v[182:183], v[86:87], v[252:253]
	v_pk_fma_f32 v[228:229], v[182:183], v[30:31], v[228:229]
	v_pk_fma_f32 v[230:231], v[182:183], v[26:27], v[230:231]
	v_pk_fma_f32 v[252:253], v[202:203], v[26:27], v[252:253]
	v_pk_fma_f32 v[228:229], v[202:203], v[74:75], v[228:229]
	v_fmac_f32_dpp v218, v74, v182 row_shr:1 row_mask:0xf bank_mask:0xf bound_ctrl:1
	v_fmac_f32_dpp v230, v86, v202 row_shl:1 row_mask:0xf bank_mask:0xf bound_ctrl:1
	v_fmac_f32_dpp v219, v75, v183 row_shr:1 row_mask:0xf bank_mask:0xf bound_ctrl:1
	v_fmac_f32_dpp v231, v87, v203 row_shl:1 row_mask:0xf bank_mask:0xf bound_ctrl:1
	v_pk_mul_f32 v[142:143], v[142:143], v[218:219]
	v_pk_mul_f32 v[178:179], v[178:179], v[252:253]
	v_pk_mul_f32 v[210:211], v[210:211], v[228:229]
	v_pk_mul_f32 v[212:213], v[212:213], v[230:231]
	v_cvt_pk_bf16_f32 v237, v142, v143
	v_cvt_pk_bf16_f32 v241, v178, v179
	v_cvt_pk_bf16_f32 v245, v210, v211
	v_cvt_pk_bf16_f32 v249, v212, v213
	v_pk_fma_f32 v[142:143], v[156:157], v[88:89], v[172:173]
	v_pk_fma_f32 v[178:179], v[156:157], v[12:13], v[172:173]
	v_pk_fma_f32 v[210:211], v[156:157], v[4:5], v[172:173]
	v_pk_fma_f32 v[212:213], v[156:157], v[56:57], v[172:173]
	v_pk_fma_f32 v[142:143], v[164:165], v[12:13], v[142:143]
	v_pk_fma_f32 v[178:179], v[148:149], v[88:89], v[178:179]
	v_pk_fma_f32 v[210:211], v[148:149], v[12:13], v[210:211]
	v_pk_fma_f32 v[212:213], v[148:149], v[4:5], v[212:213]
	v_pk_fma_f32 v[178:179], v[164:165], v[4:5], v[178:179]
	v_pk_fma_f32 v[210:211], v[164:165], v[56:57], v[210:211]
	v_fmac_f32_dpp v142, v56, v148 row_shr:1 row_mask:0xf bank_mask:0xf bound_ctrl:1
	v_fmac_f32_dpp v212, v88, v164 row_shl:1 row_mask:0xf bank_mask:0xf bound_ctrl:1
	v_fmac_f32_dpp v143, v57, v149 row_shr:1 row_mask:0xf bank_mask:0xf bound_ctrl:1
	v_fmac_f32_dpp v213, v89, v165 row_shl:1 row_mask:0xf bank_mask:0xf bound_ctrl:1
	v_pk_mul_f32 v[218:219], v[142:143], s[54:55] op_sel_hi:[1,0]
	v_pk_mul_f32 v[252:253], v[178:179], s[54:55] op_sel_hi:[1,0]
	v_pk_mul_f32 v[228:229], v[210:211], s[54:55] op_sel_hi:[1,0]
	v_pk_mul_f32 v[230:231], v[212:213], s[54:55] op_sel_hi:[1,0]
	v_exp_f32_e32 v218, v218
	v_exp_f32_e32 v219, v219
	v_exp_f32_e32 v252, v252
	v_exp_f32_e32 v253, v253
	v_exp_f32_e32 v228, v228
	v_exp_f32_e32 v229, v229
	v_exp_f32_e32 v230, v230
	v_exp_f32_e32 v231, v231
	v_pk_add_f32 v[218:219], v[218:219], s[56:57] op_sel_hi:[1,0]
	v_pk_add_f32 v[252:253], v[252:253], s[56:57] op_sel_hi:[1,0]
	v_pk_add_f32 v[228:229], v[228:229], s[56:57] op_sel_hi:[1,0]
	v_pk_add_f32 v[230:231], v[230:231], s[56:57] op_sel_hi:[1,0]
	v_rcp_f32_e32 v218, v218
	v_rcp_f32_e32 v219, v219
	v_rcp_f32_e32 v252, v252
	v_rcp_f32_e32 v253, v253
	v_rcp_f32_e32 v228, v228
	v_rcp_f32_e32 v229, v229
	v_rcp_f32_e32 v230, v230
	v_rcp_f32_e32 v231, v231
	v_pk_mul_f32 v[142:143], v[142:143], v[218:219]
	v_pk_mul_f32 v[178:179], v[178:179], v[252:253]
	v_pk_mul_f32 v[210:211], v[210:211], v[228:229]
	v_pk_mul_f32 v[212:213], v[212:213], v[230:231]
	v_pk_fma_f32 v[218:219], v[196:197], v[80:81], v[224:225]
	v_pk_fma_f32 v[252:253], v[196:197], v[8:9], v[224:225]
	v_pk_fma_f32 v[228:229], v[196:197], v[0:1], v[224:225]
	v_pk_fma_f32 v[230:231], v[196:197], v[40:41], v[224:225]
	v_pk_fma_f32 v[218:219], v[204:205], v[8:9], v[218:219]
; __device__ __forceinline__ unsigned cvt_pk_bf16(float lo, float hi) { unsigned r; asm volatile("v_cvt_pk_bf16_f32 %0, %1, %2" : "=v"(r) : "v"(lo), "v"(hi)); return r; }
; template <int CTRL> __device__ __forceinline__ float dppz(float v) { return __int_as_float(__builtin_amdgcn_update_dpp(0, __float_as_int(v), CTRL, 0xf, 0xf, true)); }
;     __device__ __forceinline__ void operator()(f32x4 (&acc)[2][2][4][2], const Unit& u, int wr, int wc, int fr, int fq, const LAS float* rtab) const {
;     ...
;                     for (int jj = 0; jj < 4; ++jj) {
;                         const float gc = acc[ai][0][m][n][jj], uc = acc[ai][1][m][n][jj];
;                         const float gb = m > 0 ? acc[ai][0][m - 1][n][jj] : 0.f, ga = m < 3 ? acc[ai][0][m + 1][n][jj] : 0.f;
;                         const float ub = m > 0 ? acc[ai][1][m - 1][n][jj] : 0.f, ua = m < 3 ? acc[ai][1][m + 1][n][jj] : 0.f;
;                         const float gp = dppz<0x111>(gc) + dppz<0x10F>(gb), gn = dppz<0x101>(gc) + dppz<0x11F>(ga);
;                         const float up = dppz<0x111>(uc) + dppz<0x10F>(ub), un = dppz<0x101>(uc) + dppz<0x11F>(ua);
;                         const float hg = wg0[jj] * gp + wg1[jj] * gc + wg2[jj] * gn + bg[jj];
;                         const float hu = wu0[jj] * up + wu1[jj] * uc + wu2[jj] * un + bu[jj];
;                         const float sg = __builtin_amdgcn_rcpf(1.f + __builtin_amdgcn_exp2f(-1.4426950408889634f * hg));
;                         y[jj] = hg * sg * hu; }
;                     u32x2 pk; pk.x = cvt_pk_bf16(y[0], y[1]); pk.y = cvt_pk_bf16(y[2], y[3]);
;                     if (n == 0) ypk[ai][m] = pk;
;                     else {
;                         const bool deferred = (m == 0 && fr == 0) || (m == 3 && fr == 15);
;                         if (!deferred) { u32x4 w; w.x = ypk[ai][m].x; w.y = ypk[ai][m].y; w.z = pk.x; w.w = pk.y; *(u32x4*)(act + (size_t)(r64 + m * 16 + fr) * DFF + c0) = w; } }
	v_pk_fma_f32 v[252:253], v[184:185], v[80:81], v[252:253]
	v_pk_fma_f32 v[228:229], v[184:185], v[8:9], v[228:229]
	v_pk_fma_f32 v[230:231], v[184:185], v[0:1], v[230:231]
	v_pk_fma_f32 v[252:253], v[204:205], v[0:1], v[252:253]
	v_pk_fma_f32 v[228:229], v[204:205], v[40:41], v[228:229]
	v_fmac_f32_dpp v218, v40, v184 row_shr:1 row_mask:0xf bank_mask:0xf bound_ctrl:1
	v_fmac_f32_dpp v230, v80, v204 row_shl:1 row_mask:0xf bank_mask:0xf bound_ctrl:1
	v_fmac_f32_dpp v219, v41, v185 row_shr:1 row_mask:0xf bank_mask:0xf bound_ctrl:1
	v_fmac_f32_dpp v231, v81, v205 row_shl:1 row_mask:0xf bank_mask:0xf bound_ctrl:1
	v_pk_mul_f32 v[142:143], v[142:143], v[218:219]
	v_pk_mul_f32 v[178:179], v[178:179], v[252:253]
	v_pk_mul_f32 v[210:211], v[210:211], v[228:229]
	v_pk_mul_f32 v[212:213], v[212:213], v[230:231]
	v_cvt_pk_bf16_f32 v238, v142, v143
	v_cvt_pk_bf16_f32 v242, v178, v179
	v_cvt_pk_bf16_f32 v246, v210, v211
	v_cvt_pk_bf16_f32 v250, v212, v213
	v_pk_fma_f32 v[142:143], v[158:159], v[90:91], v[174:175]
	v_pk_fma_f32 v[178:179], v[158:159], v[14:15], v[174:175]
	v_pk_fma_f32 v[210:211], v[158:159], v[6:7], v[174:175]
	v_pk_fma_f32 v[212:213], v[158:159], v[58:59], v[174:175]
	v_pk_fma_f32 v[142:143], v[166:167], v[14:15], v[142:143]
	v_pk_fma_f32 v[178:179], v[150:151], v[90:91], v[178:179]
	v_pk_fma_f32 v[210:211], v[150:151], v[14:15], v[210:211]
	v_pk_fma_f32 v[212:213], v[150:151], v[6:7], v[212:213]
	v_pk_fma_f32 v[178:179], v[166:167], v[6:7], v[178:179]
	v_pk_fma_f32 v[210:211], v[166:167], v[58:59], v[210:211]
	v_fmac_f32_dpp v142, v58, v150 row_shr:1 row_mask:0xf bank_mask:0xf bound_ctrl:1
	v_fmac_f32_dpp v212, v90, v166 row_shl:1 row_mask:0xf bank_mask:0xf bound_ctrl:1
	v_fmac_f32_dpp v143, v59, v151 row_shr:1 row_mask:0xf bank_mask:0xf bound_ctrl:1
	v_fmac_f32_dpp v213, v91, v167 row_shl:1 row_mask:0xf bank_mask:0xf bound_ctrl:1
	v_pk_mul_f32 v[218:219], v[142:143], s[54:55] op_sel_hi:[1,0]
	v_pk_mul_f32 v[252:253], v[178:179], s[54:55] op_sel_hi:[1,0]
	v_pk_mul_f32 v[228:229], v[210:211], s[54:55] op_sel_hi:[1,0]
	v_pk_mul_f32 v[230:231], v[212:213], s[54:55] op_sel_hi:[1,0]
	v_exp_f32_e32 v218, v218
	v_exp_f32_e32 v219, v219
	v_exp_f32_e32 v252, v252
	v_exp_f32_e32 v253, v253
	v_exp_f32_e32 v228, v228
	v_exp_f32_e32 v229, v229
	v_exp_f32_e32 v230, v230
	v_exp_f32_e32 v231, v231
	v_pk_add_f32 v[218:219], v[218:219], s[56:57] op_sel_hi:[1,0]
	v_pk_add_f32 v[252:253], v[252:253], s[56:57] op_sel_hi:[1,0]
	v_pk_add_f32 v[228:229], v[228:229], s[56:57] op_sel_hi:[1,0]
	v_pk_add_f32 v[230:231], v[230:231], s[56:57] op_sel_hi:[1,0]
	v_rcp_f32_e32 v218, v218
	v_rcp_f32_e32 v219, v219
	v_rcp_f32_e32 v252, v252
	v_rcp_f32_e32 v253, v253
	v_rcp_f32_e32 v228, v228
	v_rcp_f32_e32 v229, v229
	v_rcp_f32_e32 v230, v230
	v_rcp_f32_e32 v231, v231
	v_pk_mul_f32 v[142:143], v[142:143], v[218:219]
	v_pk_mul_f32 v[178:179], v[178:179], v[252:253]
	v_pk_mul_f32 v[210:211], v[210:211], v[228:229]
	v_pk_mul_f32 v[212:213], v[212:213], v[230:231]
	v_pk_fma_f32 v[218:219], v[198:199], v[82:83], v[226:227]
	v_pk_fma_f32 v[252:253], v[198:199], v[10:11], v[226:227]
	v_pk_fma_f32 v[228:229], v[198:199], v[2:3], v[226:227]
	v_pk_fma_f32 v[230:231], v[198:199], v[42:43], v[226:227]
	v_pk_fma_f32 v[218:219], v[206:207], v[10:11], v[218:219]
	v_pk_fma_f32 v[252:253], v[186:187], v[82:83], v[252:253]
	v_pk_fma_f32 v[228:229], v[186:187], v[10:11], v[228:229]
	v_pk_fma_f32 v[230:231], v[186:187], v[2:3], v[230:231]
	v_pk_fma_f32 v[252:253], v[206:207], v[2:3], v[252:253]
	v_pk_fma_f32 v[228:229], v[206:207], v[42:43], v[228:229]
	v_fmac_f32_dpp v218, v42, v186 row_shr:1 row_mask:0xf bank_mask:0xf bound_ctrl:1
	v_fmac_f32_dpp v230, v82, v206 row_shl:1 row_mask:0xf bank_mask:0xf bound_ctrl:1
	v_fmac_f32_dpp v219, v43, v187 row_shr:1 row_mask:0xf bank_mask:0xf bound_ctrl:1
	v_fmac_f32_dpp v231, v83, v207 row_shl:1 row_mask:0xf bank_mask:0xf bound_ctrl:1
	v_pk_mul_f32 v[142:143], v[142:143], v[218:219]
	v_pk_mul_f32 v[178:179], v[178:179], v[252:253]
	v_pk_mul_f32 v[210:211], v[210:211], v[228:229]
	v_pk_mul_f32 v[212:213], v[212:213], v[230:231]
	v_cvt_pk_bf16_f32 v239, v142, v143
	v_cvt_pk_bf16_f32 v243, v178, v179
	v_cvt_pk_bf16_f32 v247, v210, v211
	v_cvt_pk_bf16_f32 v251, v212, v213
	s_add_u32 s58, s28, 0x160000
	s_addc_u32 s59, s29, 0
	s_mov_b64 exec, s[12:13]
	global_store_dwordx4 v234, v[236:239], s[58:59]
	s_mov_b64 exec, -1
	s_add_u32 s58, s28, 0x162c00
	s_addc_u32 s59, s29, 0
	global_store_dwordx4 v234, v[240:243], s[58:59]
	s_add_u32 s58, s28, 0x165800
	s_addc_u32 s59, s29, 0
	global_store_dwordx4 v234, v[244:247], s[58:59]
	s_add_u32 s58, s28, 0x168400
	s_addc_u32 s59, s29, 0
	s_mov_b64 exec, s[10:11]
	global_store_dwordx4 v234, v[248:251], s[58:59]
	s_mov_b64 exec, -1
	s_andn2_b64 vcc, exec, s[52:53]
	s_mov_b64 s[52:53], -1
	s_cbranch_vccnz .LBB0_834
